# norm phases: 64-lane sum of squares via row-rotate DPP adds + 4-term cross-row add instead of six dependent ds_bpermute round trips (f32, different association order)
# baseline (speedup 1.0000x reference)
; __device__ __forceinline__ unsigned pk2(float lo, float hi) { return f2bf(lo) | (f2bf(hi) << 16); }
; __device__ __forceinline__ float wave_sum(float v) {
; #pragma unroll
;     for (int o = 1; o < 64; o <<= 1) v += __shfl_xor(v, o);
;     return v;
; __device__ __forceinline__ void norm_phase(const float* src, const float* gain, const float* mod_l, int sh_off, int sc_off, bf16_t* dst) {
;     ...
;     for (int row = r0; row < r1; ++row) {
;         const int b = row >> 12;
;         if (b != cur_b) { const float* mb = mod_l + (size_t)b * 6144;
; #pragma unroll
;             for (int j = 0; j < 4; ++j) { const int col = 4 * lane + 256 * j;
;                 cs[j] = *(const f32x4*)(gain + col) * (*(const f32x4*)(mb + sc_off + col) + 1.f); sh[j] = *(const f32x4*)(mb + sh_off + col); }
;             cur_b = b; }
;         f32x4 v[4]; float ss = 0.f;
; #pragma unroll
;         for (int j = 0; j < 4; ++j) { v[j] = vn[j]; vn[j] = vm[j]; }
;         if (row + 2 < r1) { const f32x4* xn = (const f32x4*)(src + (size_t)(row + 2) * DM) + lane;
; #pragma unroll
;             for (int j = 0; j < 4; ++j) vm[j] = xn[64 * j]; }
; #pragma unroll
;         for (int j = 0; j < 4; ++j) ss += (v[j].x * v[j].x + v[j].y * v[j].y) + (v[j].z * v[j].z + v[j].w * v[j].w);
;         const float r = rsqrtf(wave_sum(ss) * (1.f / DM) + RMS_EPS);
;         u32x2* o8 = (u32x2*)(dst + (size_t)row * DM) + lane;
; #pragma unroll
;         for (int j = 0; j < 4; ++j) { const f32x4 y = v[j] * r * cs[j] + sh[j];
;             u32x2 o; o.x = pk2(y[0], y[1]); o.y = pk2(y[2], y[3]); o8[64 * j] = o; }
;     }
.LBB0_127:
	s_or_b64 exec, exec, s[14:15]
	v_pk_mul_f32 v[96:97], v[12:13], v[12:13]
	v_pk_mul_f32 v[106:107], v[14:15], v[14:15]
	v_pk_mul_f32 v[108:109], v[16:17], v[16:17]
	v_pk_mul_f32 v[110:111], v[18:19], v[18:19]
	v_mov_b32_e32 v112, v108
	v_mov_b32_e32 v113, v111
	v_pk_mov_b32 v[108:109], v[108:109], v[110:111] op_sel:[1,0]
	v_mov_b32_e32 v110, v96
	v_mov_b32_e32 v111, v107
	v_pk_mov_b32 v[96:97], v[96:97], v[106:107] op_sel:[1,0]
	v_pk_add_f32 v[108:109], v[108:109], v[112:113]
	v_pk_add_f32 v[96:97], v[96:97], v[110:111]
	v_pk_add_f32 v[108:109], v[108:109], v[108:109] op_sel_hi:[0,1]
	v_pk_add_f32 v[96:97], v[96:97], v[96:97] op_sel_hi:[0,1]
	v_mul_f32_e32 v96, v8, v8
	v_pk_fma_f32 v[106:107], v[8:9], v[8:9], v[96:97] op_sel_hi:[1,1,0]
	v_mul_f32_e32 v96, v10, v10
	v_pk_fma_f32 v[110:111], v[10:11], v[10:11], v[96:97] op_sel_hi:[1,1,0]
	v_mul_f32_e32 v106, v4, v4
	v_mul_f32_e32 v110, v5, v5
	v_mul_f32_e32 v108, v6, v6
	v_mul_f32_e32 v96, v7, v7
	v_pk_add_f32 v[106:107], v[106:107], v[110:111]
	v_pk_add_f32 v[96:97], v[108:109], v[96:97]
	v_add_u32_e32 v80, 1, v80
	v_pk_add_f32 v[96:97], v[106:107], v[96:97]
	s_nop 0
	v_add_f32_e32 v93, v96, v97
	s_nop 1
	v_add_f32_dpp v93, v93, v93 row_ror:8 row_mask:0xf bank_mask:0xf
	s_nop 1
	v_add_f32_dpp v93, v93, v93 row_ror:4 row_mask:0xf bank_mask:0xf
	s_nop 1
	v_add_f32_dpp v93, v93, v93 row_ror:2 row_mask:0xf bank_mask:0xf
	s_nop 1
	v_add_f32_dpp v93, v93, v93 row_ror:1 row_mask:0xf bank_mask:0xf
	s_nop 1
	v_readlane_b32 s32, v93, 0
	v_readlane_b32 s98, v93, 16
	v_readlane_b32 s99, v93, 32
	v_readlane_b32 s100, v93, 48
	s_nop 0
	v_mov_b32_e32 v93, s32
	v_add_f32_e32 v93, s98, v93
	v_add_f32_e32 v93, s99, v93
	v_add_f32_e32 v93, s100, v93
	v_fmamk_f32 v93, v93, 0x3a800000, v81
	v_mul_f32_e32 v95, 0x4b800000, v93
	v_cmp_gt_f32_e32 vcc, s0, v93
	s_nop 1
	v_cndmask_b32_e32 v93, v93, v95, vcc
	v_rsq_f32_e32 v93, v93
	s_nop 0
	v_mul_f32_e32 v95, 0x45800000, v93
	v_cndmask_b32_e32 v96, v93, v95, vcc
	v_pk_mul_f32 v[16:17], v[16:17], v[96:97] op_sel_hi:[1,0]
	v_pk_mul_f32 v[18:19], v[18:19], v[96:97] op_sel_hi:[1,0]
	v_pk_fma_f32 v[16:17], v[48:49], v[16:17], v[32:33]
	v_pk_fma_f32 v[18:19], v[50:51], v[18:19], v[34:35]
	v_bfe_u32 v93, v16, 16, 1
	v_bfe_u32 v95, v17, 16, 1
	v_bfe_u32 v97, v18, 16, 1
	v_add3_u32 v16, v16, v93, s1
	v_bfe_u32 v105, v19, 16, 1
	v_add3_u32 v17, v17, v95, s1
	v_add3_u32 v18, v18, v97, s1
	v_lshrrev_b32_e32 v16, 16, v16
	v_lshrrev_b32_e32 v18, 16, v18
	v_and_or_b32 v16, v17, s2, v16
	v_add3_u32 v17, v19, v105, s1
	v_pk_mul_f32 v[12:13], v[12:13], v[96:97] op_sel_hi:[1,0]
	v_and_or_b32 v17, v17, s2, v18
	v_pk_fma_f32 v[12:13], v[52:53], v[12:13], v[40:41]
	global_store_dwordx2 v[88:89], v[16:17], off
	v_bfe_u32 v16, v12, 16, 1
	v_pk_mul_f32 v[14:15], v[14:15], v[96:97] op_sel_hi:[1,0]
	v_add3_u32 v12, v12, v16, s1
	v_bfe_u32 v16, v13, 16, 1
	v_pk_fma_f32 v[14:15], v[54:55], v[14:15], v[42:43]
	v_lshrrev_b32_e32 v12, 16, v12
	v_add3_u32 v13, v13, v16, s1
	v_and_or_b32 v12, v13, s2, v12
	v_bfe_u32 v13, v14, 16, 1
	v_add3_u32 v13, v14, v13, s1
	v_bfe_u32 v14, v15, 16, 1
	v_lshrrev_b32_e32 v13, 16, v13
	v_add3_u32 v14, v15, v14, s1
	v_pk_mul_f32 v[8:9], v[8:9], v[96:97] op_sel_hi:[1,0]
	v_and_or_b32 v13, v14, s2, v13
	v_pk_fma_f32 v[8:9], v[56:57], v[8:9], v[36:37]
	global_store_dwordx2 v[88:89], v[12:13], off offset:512
	v_bfe_u32 v12, v8, 16, 1
	v_pk_mul_f32 v[10:11], v[10:11], v[96:97] op_sel_hi:[1,0]
	v_add3_u32 v8, v8, v12, s1
	v_bfe_u32 v12, v9, 16, 1
	v_pk_fma_f32 v[10:11], v[58:59], v[10:11], v[38:39]
	v_lshrrev_b32_e32 v8, 16, v8
	v_add3_u32 v9, v9, v12, s1
	v_and_or_b32 v8, v9, s2, v8
	v_bfe_u32 v9, v10, 16, 1
	v_add3_u32 v9, v10, v9, s1
	v_bfe_u32 v10, v11, 16, 1
	v_lshrrev_b32_e32 v9, 16, v9
	v_add3_u32 v10, v11, v10, s1
	v_pk_mul_f32 v[4:5], v[4:5], v[96:97] op_sel_hi:[1,0]
	v_and_or_b32 v9, v10, s2, v9
	v_pk_fma_f32 v[4:5], v[60:61], v[4:5], v[44:45]
	global_store_dwordx2 v[88:89], v[8:9], off offset:1024
	v_bfe_u32 v8, v4, 16, 1
	v_pk_mul_f32 v[6:7], v[6:7], v[96:97] op_sel_hi:[1,0]
	v_add3_u32 v4, v4, v8, s1
	v_bfe_u32 v8, v5, 16, 1
	v_pk_fma_f32 v[6:7], v[62:63], v[6:7], v[46:47]
	v_lshrrev_b32_e32 v4, 16, v4
	v_add3_u32 v5, v5, v8, s1
	v_and_or_b32 v4, v5, s2, v4
	v_bfe_u32 v5, v6, 16, 1
	v_add3_u32 v5, v6, v5, s1
	v_bfe_u32 v6, v7, 16, 1
	v_lshrrev_b32_e32 v5, 16, v5
	v_add3_u32 v6, v7, v6, s1
	v_and_or_b32 v5, v6, s2, v5
	global_store_dwordx2 v[88:89], v[4:5], off offset:1536
	v_mov_b32_e32 v16, v28
	v_mov_b32_e32 v17, v29
	v_mov_b32_e32 v18, v30
	v_mov_b32_e32 v19, v31
	v_mov_b32_e32 v12, v24
	v_mov_b32_e32 v13, v25
	v_mov_b32_e32 v14, v26
	v_mov_b32_e32 v15, v27
	v_mov_b32_e32 v8, v20
	v_mov_b32_e32 v9, v21
	v_mov_b32_e32 v10, v22
	v_mov_b32_e32 v11, v23
	v_mov_b32_e32 v4, v0
	v_mov_b32_e32 v5, v1
	v_mov_b32_e32 v6, v2
	v_mov_b32_e32 v7, v3
	v_cmp_ge_i32_e32 vcc, v80, v98
	s_waitcnt vmcnt(4)
	v_mov_b64_e32 v[0:1], v[76:77]
	v_mov_b64_e32 v[20:21], v[72:73]
	v_mov_b64_e32 v[24:25], v[68:69]
	v_mov_b64_e32 v[28:29], v[64:65]
	v_lshl_add_u64 v[88:89], v[88:89], 0, s[10:11]
	s_or_b64 s[6:7], vcc, s[6:7]
	v_mov_b64_e32 v[2:3], v[78:79]
	v_mov_b64_e32 v[22:23], v[74:75]
	v_mov_b64_e32 v[26:27], v[70:71]
	v_mov_b64_e32 v[30:31], v[66:67]
	s_andn2_b64 exec, exec, s[6:7]
	s_cbranch_execz .LBB0_132

; __device__ __forceinline__ unsigned pk2(float lo, float hi) { return f2bf(lo) | (f2bf(hi) << 16); }
; __device__ __forceinline__ float wave_sum(float v) {
; #pragma unroll
;     for (int o = 1; o < 64; o <<= 1) v += __shfl_xor(v, o);
;     return v;
; __device__ __forceinline__ void norm_phase(const float* src, const float* gain, const float* mod_l, int sh_off, int sc_off, bf16_t* dst) {
;     ...
;     for (int row = r0; row < r1; ++row) {
;         const int b = row >> 12;
;         if (b != cur_b) { const float* mb = mod_l + (size_t)b * 6144;
; #pragma unroll
;             for (int j = 0; j < 4; ++j) { const int col = 4 * lane + 256 * j;
;                 cs[j] = *(const f32x4*)(gain + col) * (*(const f32x4*)(mb + sc_off + col) + 1.f); sh[j] = *(const f32x4*)(mb + sh_off + col); }
;             cur_b = b; }
;         f32x4 v[4]; float ss = 0.f;
; #pragma unroll
;         for (int j = 0; j < 4; ++j) { v[j] = vn[j]; vn[j] = vm[j]; }
;         if (row + 2 < r1) { const f32x4* xn = (const f32x4*)(src + (size_t)(row + 2) * DM) + lane;
; #pragma unroll
;             for (int j = 0; j < 4; ++j) vm[j] = xn[64 * j]; }
; #pragma unroll
;         for (int j = 0; j < 4; ++j) ss += (v[j].x * v[j].x + v[j].y * v[j].y) + (v[j].z * v[j].z + v[j].w * v[j].w);
;         const float r = rsqrtf(wave_sum(ss) * (1.f / DM) + RMS_EPS);
;         u32x2* o8 = (u32x2*)(dst + (size_t)row * DM) + lane;
; #pragma unroll
;         for (int j = 0; j < 4; ++j) { const f32x4 y = v[j] * r * cs[j] + sh[j];
;             u32x2 o; o.x = pk2(y[0], y[1]); o.y = pk2(y[2], y[3]); o8[64 * j] = o; }
;     }
.LBB0_419:
	s_or_b64 exec, exec, s[16:17]
	v_pk_mul_f32 v[96:97], v[12:13], v[12:13]
	v_pk_mul_f32 v[106:107], v[14:15], v[14:15]
	v_pk_mul_f32 v[108:109], v[16:17], v[16:17]
	v_pk_mul_f32 v[110:111], v[18:19], v[18:19]
	v_mov_b32_e32 v112, v108
	v_mov_b32_e32 v113, v111
	v_pk_mov_b32 v[108:109], v[108:109], v[110:111] op_sel:[1,0]
	v_mov_b32_e32 v110, v96
	v_mov_b32_e32 v111, v107
	v_pk_mov_b32 v[96:97], v[96:97], v[106:107] op_sel:[1,0]
	v_pk_add_f32 v[108:109], v[108:109], v[112:113]
	v_pk_add_f32 v[96:97], v[96:97], v[110:111]
	v_pk_add_f32 v[108:109], v[108:109], v[108:109] op_sel_hi:[0,1]
	v_pk_add_f32 v[96:97], v[96:97], v[96:97] op_sel_hi:[0,1]
	v_mul_f32_e32 v96, v8, v8
	v_pk_fma_f32 v[106:107], v[8:9], v[8:9], v[96:97] op_sel_hi:[1,1,0]
	v_mul_f32_e32 v96, v10, v10
	v_pk_fma_f32 v[110:111], v[10:11], v[10:11], v[96:97] op_sel_hi:[1,1,0]
	v_mul_f32_e32 v106, v4, v4
	v_mul_f32_e32 v110, v5, v5
	v_mul_f32_e32 v108, v6, v6
	v_mul_f32_e32 v96, v7, v7
	v_pk_add_f32 v[106:107], v[106:107], v[110:111]
	v_pk_add_f32 v[96:97], v[108:109], v[96:97]
	v_add_u32_e32 v80, 1, v80
	v_pk_add_f32 v[96:97], v[106:107], v[96:97]
	s_nop 0
	v_add_f32_e32 v93, v96, v97
	s_nop 1
	v_add_f32_dpp v93, v93, v93 row_ror:8 row_mask:0xf bank_mask:0xf
	s_nop 1
	v_add_f32_dpp v93, v93, v93 row_ror:4 row_mask:0xf bank_mask:0xf
	s_nop 1
	v_add_f32_dpp v93, v93, v93 row_ror:2 row_mask:0xf bank_mask:0xf
	s_nop 1
	v_add_f32_dpp v93, v93, v93 row_ror:1 row_mask:0xf bank_mask:0xf
	s_nop 1
	v_readlane_b32 s32, v93, 0
	v_readlane_b32 s98, v93, 16
	v_readlane_b32 s99, v93, 32
	v_readlane_b32 s100, v93, 48
	s_nop 0
	v_mov_b32_e32 v93, s32
	v_add_f32_e32 v93, s98, v93
	v_add_f32_e32 v93, s99, v93
	v_add_f32_e32 v93, s100, v93
	v_fmamk_f32 v93, v93, 0x3a800000, v81
	v_mul_f32_e32 v95, 0x4b800000, v93
	v_cmp_gt_f32_e32 vcc, s0, v93
	s_nop 1
	v_cndmask_b32_e32 v93, v93, v95, vcc
	v_rsq_f32_e32 v93, v93
	s_nop 0
	v_mul_f32_e32 v95, 0x45800000, v93
	v_cndmask_b32_e32 v96, v93, v95, vcc
	v_pk_mul_f32 v[16:17], v[16:17], v[96:97] op_sel_hi:[1,0]
	v_pk_mul_f32 v[18:19], v[18:19], v[96:97] op_sel_hi:[1,0]
	v_pk_fma_f32 v[16:17], v[48:49], v[16:17], v[32:33]
	v_pk_fma_f32 v[18:19], v[50:51], v[18:19], v[34:35]
	v_bfe_u32 v93, v16, 16, 1
	v_bfe_u32 v95, v17, 16, 1
	v_bfe_u32 v97, v18, 16, 1
	v_add3_u32 v16, v16, v93, s1
	v_bfe_u32 v105, v19, 16, 1
	v_add3_u32 v17, v17, v95, s1
	v_add3_u32 v18, v18, v97, s1
	v_lshrrev_b32_e32 v16, 16, v16
	v_lshrrev_b32_e32 v18, 16, v18
	v_and_or_b32 v16, v17, s2, v16
	v_add3_u32 v17, v19, v105, s1
	v_pk_mul_f32 v[12:13], v[12:13], v[96:97] op_sel_hi:[1,0]
	v_and_or_b32 v17, v17, s2, v18
	v_pk_fma_f32 v[12:13], v[52:53], v[12:13], v[36:37]
	global_store_dwordx2 v[88:89], v[16:17], off
	v_bfe_u32 v16, v12, 16, 1
	v_pk_mul_f32 v[14:15], v[14:15], v[96:97] op_sel_hi:[1,0]
	v_add3_u32 v12, v12, v16, s1
	v_bfe_u32 v16, v13, 16, 1
	v_pk_fma_f32 v[14:15], v[54:55], v[14:15], v[38:39]
	v_lshrrev_b32_e32 v12, 16, v12
	v_add3_u32 v13, v13, v16, s1
	v_and_or_b32 v12, v13, s2, v12
	v_bfe_u32 v13, v14, 16, 1
	v_add3_u32 v13, v14, v13, s1
	v_bfe_u32 v14, v15, 16, 1
	v_lshrrev_b32_e32 v13, 16, v13
	v_add3_u32 v14, v15, v14, s1
	v_pk_mul_f32 v[8:9], v[8:9], v[96:97] op_sel_hi:[1,0]
	v_and_or_b32 v13, v14, s2, v13
	v_pk_fma_f32 v[8:9], v[56:57], v[8:9], v[40:41]
	global_store_dwordx2 v[88:89], v[12:13], off offset:512
	v_bfe_u32 v12, v8, 16, 1
	v_pk_mul_f32 v[10:11], v[10:11], v[96:97] op_sel_hi:[1,0]
	v_add3_u32 v8, v8, v12, s1
	v_bfe_u32 v12, v9, 16, 1
	v_pk_fma_f32 v[10:11], v[58:59], v[10:11], v[42:43]
	v_lshrrev_b32_e32 v8, 16, v8
	v_add3_u32 v9, v9, v12, s1
	v_and_or_b32 v8, v9, s2, v8
	v_bfe_u32 v9, v10, 16, 1
	v_add3_u32 v9, v10, v9, s1
	v_bfe_u32 v10, v11, 16, 1
	v_lshrrev_b32_e32 v9, 16, v9
	v_add3_u32 v10, v11, v10, s1
	v_pk_mul_f32 v[4:5], v[4:5], v[96:97] op_sel_hi:[1,0]
	v_and_or_b32 v9, v10, s2, v9
	v_pk_fma_f32 v[4:5], v[60:61], v[4:5], v[44:45]
	global_store_dwordx2 v[88:89], v[8:9], off offset:1024
	v_bfe_u32 v8, v4, 16, 1
	v_pk_mul_f32 v[6:7], v[6:7], v[96:97] op_sel_hi:[1,0]
	v_add3_u32 v4, v4, v8, s1
	v_bfe_u32 v8, v5, 16, 1
	v_pk_fma_f32 v[6:7], v[62:63], v[6:7], v[46:47]
	v_lshrrev_b32_e32 v4, 16, v4
	v_add3_u32 v5, v5, v8, s1
	v_and_or_b32 v4, v5, s2, v4
	v_bfe_u32 v5, v6, 16, 1
	v_add3_u32 v5, v6, v5, s1
	v_bfe_u32 v6, v7, 16, 1
	v_lshrrev_b32_e32 v5, 16, v5
	v_add3_u32 v6, v7, v6, s1
	v_and_or_b32 v5, v6, s2, v5
	global_store_dwordx2 v[88:89], v[4:5], off offset:1536
	v_mov_b32_e32 v16, v28
	v_mov_b32_e32 v17, v29
	v_mov_b32_e32 v18, v30
	v_mov_b32_e32 v19, v31
	v_mov_b32_e32 v12, v24
	v_mov_b32_e32 v13, v25
	v_mov_b32_e32 v14, v26
	v_mov_b32_e32 v15, v27
	v_mov_b32_e32 v8, v20
	v_mov_b32_e32 v9, v21
	v_mov_b32_e32 v10, v22
	v_mov_b32_e32 v11, v23
	v_mov_b32_e32 v4, v0
	v_mov_b32_e32 v5, v1
	v_mov_b32_e32 v6, v2
	v_mov_b32_e32 v7, v3
	v_cmp_ge_i32_e32 vcc, v80, v98
	s_waitcnt vmcnt(4)
	v_mov_b64_e32 v[0:1], v[76:77]
	v_mov_b64_e32 v[20:21], v[72:73]
	v_mov_b64_e32 v[24:25], v[68:69]
	v_mov_b64_e32 v[28:29], v[64:65]
	v_lshl_add_u64 v[88:89], v[88:89], 0, s[14:15]
	s_or_b64 s[6:7], vcc, s[6:7]
	v_mov_b64_e32 v[2:3], v[78:79]
	v_mov_b64_e32 v[22:23], v[74:75]
	v_mov_b64_e32 v[26:27], v[70:71]
	v_mov_b64_e32 v[30:31], v[66:67]
	s_andn2_b64 exec, exec, s[6:7]
	s_cbranch_execz .LBB0_424

; __device__ __forceinline__ unsigned pk2(float lo, float hi) { return f2bf(lo) | (f2bf(hi) << 16); }
; __device__ __forceinline__ float wave_sum(float v) {
; #pragma unroll
;     for (int o = 1; o < 64; o <<= 1) v += __shfl_xor(v, o);
;     return v;
; __device__ __forceinline__ void norm_phase(const float* src, const float* gain, const float* mod_l, int sh_off, int sc_off, bf16_t* dst) {
;     ...
;     for (int row = r0; row < r1; ++row) {
;         const int b = row >> 12;
;         if (b != cur_b) { const float* mb = mod_l + (size_t)b * 6144;
; #pragma unroll
;             for (int j = 0; j < 4; ++j) { const int col = 4 * lane + 256 * j;
;                 cs[j] = *(const f32x4*)(gain + col) * (*(const f32x4*)(mb + sc_off + col) + 1.f); sh[j] = *(const f32x4*)(mb + sh_off + col); }
;             cur_b = b; }
;         f32x4 v[4]; float ss = 0.f;
; #pragma unroll
;         for (int j = 0; j < 4; ++j) { v[j] = vn[j]; vn[j] = vm[j]; }
;         if (row + 2 < r1) { const f32x4* xn = (const f32x4*)(src + (size_t)(row + 2) * DM) + lane;
; #pragma unroll
;             for (int j = 0; j < 4; ++j) vm[j] = xn[64 * j]; }
; #pragma unroll
;         for (int j = 0; j < 4; ++j) ss += (v[j].x * v[j].x + v[j].y * v[j].y) + (v[j].z * v[j].z + v[j].w * v[j].w);
;         const float r = rsqrtf(wave_sum(ss) * (1.f / DM) + RMS_EPS);
;         u32x2* o8 = (u32x2*)(dst + (size_t)row * DM) + lane;
; #pragma unroll
;         for (int j = 0; j < 4; ++j) { const f32x4 y = v[j] * r * cs[j] + sh[j];
;             u32x2 o; o.x = pk2(y[0], y[1]); o.y = pk2(y[2], y[3]); o8[64 * j] = o; }
;     }
.LBB0_731:
	s_or_b64 exec, exec, s[18:19]
	v_pk_mul_f32 v[102:103], v[12:13], v[12:13]
	v_pk_mul_f32 v[112:113], v[14:15], v[14:15]
	v_pk_mul_f32 v[114:115], v[16:17], v[16:17]
	v_pk_mul_f32 v[116:117], v[18:19], v[18:19]
	v_mov_b32_e32 v118, v114
	v_mov_b32_e32 v119, v117
	v_pk_mov_b32 v[114:115], v[114:115], v[116:117] op_sel:[1,0]
	v_mov_b32_e32 v116, v102
	v_mov_b32_e32 v117, v113
	v_pk_mov_b32 v[102:103], v[102:103], v[112:113] op_sel:[1,0]
	v_pk_add_f32 v[114:115], v[114:115], v[118:119]
	v_pk_add_f32 v[102:103], v[102:103], v[116:117]
	v_pk_add_f32 v[114:115], v[114:115], v[114:115] op_sel_hi:[0,1]
	v_pk_add_f32 v[102:103], v[102:103], v[102:103] op_sel_hi:[0,1]
	v_mul_f32_e32 v102, v8, v8
	v_pk_fma_f32 v[112:113], v[8:9], v[8:9], v[102:103] op_sel_hi:[1,1,0]
	v_mul_f32_e32 v102, v10, v10
	v_pk_fma_f32 v[116:117], v[10:11], v[10:11], v[102:103] op_sel_hi:[1,1,0]
	v_mul_f32_e32 v112, v4, v4
	v_mul_f32_e32 v116, v5, v5
	v_mul_f32_e32 v114, v6, v6
	v_mul_f32_e32 v102, v7, v7
	v_pk_add_f32 v[112:113], v[112:113], v[116:117]
	v_pk_add_f32 v[102:103], v[114:115], v[102:103]
	v_add_u32_e32 v80, 1, v80
	v_pk_add_f32 v[102:103], v[112:113], v[102:103]
	s_nop 0
	v_add_f32_e32 v99, v102, v103
	s_nop 1
	v_add_f32_dpp v99, v99, v99 row_ror:8 row_mask:0xf bank_mask:0xf
	s_nop 1
	v_add_f32_dpp v99, v99, v99 row_ror:4 row_mask:0xf bank_mask:0xf
	s_nop 1
	v_add_f32_dpp v99, v99, v99 row_ror:2 row_mask:0xf bank_mask:0xf
	s_nop 1
	v_add_f32_dpp v99, v99, v99 row_ror:1 row_mask:0xf bank_mask:0xf
	s_nop 1
	v_readlane_b32 s32, v99, 0
	v_readlane_b32 s98, v99, 16
	v_readlane_b32 s99, v99, 32
	v_readlane_b32 s100, v99, 48
	s_nop 0
	v_mov_b32_e32 v99, s32
	v_add_f32_e32 v99, s98, v99
	v_add_f32_e32 v99, s99, v99
	v_add_f32_e32 v99, s100, v99
	v_fmamk_f32 v99, v99, 0x3a800000, v81
	v_mul_f32_e32 v101, 0x4b800000, v99
	v_cmp_gt_f32_e32 vcc, s0, v99
	s_nop 1
	v_cndmask_b32_e32 v99, v99, v101, vcc
	v_rsq_f32_e32 v99, v99
	s_nop 0
	v_mul_f32_e32 v101, 0x45800000, v99
	v_cndmask_b32_e32 v102, v99, v101, vcc
	v_pk_mul_f32 v[16:17], v[16:17], v[102:103] op_sel_hi:[1,0]
	v_pk_mul_f32 v[18:19], v[18:19], v[102:103] op_sel_hi:[1,0]
	v_pk_fma_f32 v[16:17], v[48:49], v[16:17], v[32:33]
	v_pk_fma_f32 v[18:19], v[50:51], v[18:19], v[34:35]
	v_bfe_u32 v99, v16, 16, 1
	v_bfe_u32 v101, v17, 16, 1
	v_bfe_u32 v103, v18, 16, 1
	v_add3_u32 v16, v16, v99, s1
	v_bfe_u32 v111, v19, 16, 1
	v_add3_u32 v17, v17, v101, s1
	v_add3_u32 v18, v18, v103, s1
	v_lshrrev_b32_e32 v16, 16, v16
	v_lshrrev_b32_e32 v18, 16, v18
	v_and_or_b32 v16, v17, s2, v16
	v_add3_u32 v17, v19, v111, s1
	v_pk_mul_f32 v[12:13], v[12:13], v[102:103] op_sel_hi:[1,0]
	v_and_or_b32 v17, v17, s2, v18
	v_pk_fma_f32 v[12:13], v[52:53], v[12:13], v[40:41]
	global_store_dwordx2 v[94:95], v[16:17], off
	v_bfe_u32 v16, v12, 16, 1
	v_pk_mul_f32 v[14:15], v[14:15], v[102:103] op_sel_hi:[1,0]
	v_add3_u32 v12, v12, v16, s1
	v_bfe_u32 v16, v13, 16, 1
	v_pk_fma_f32 v[14:15], v[54:55], v[14:15], v[42:43]
	v_lshrrev_b32_e32 v12, 16, v12
	v_add3_u32 v13, v13, v16, s1
	v_and_or_b32 v12, v13, s2, v12
	v_bfe_u32 v13, v14, 16, 1
	v_add3_u32 v13, v14, v13, s1
	v_bfe_u32 v14, v15, 16, 1
	v_lshrrev_b32_e32 v13, 16, v13
	v_add3_u32 v14, v15, v14, s1
	v_pk_mul_f32 v[8:9], v[8:9], v[102:103] op_sel_hi:[1,0]
	v_and_or_b32 v13, v14, s2, v13
	v_pk_fma_f32 v[8:9], v[56:57], v[8:9], v[36:37]
	global_store_dwordx2 v[94:95], v[12:13], off offset:512
	v_bfe_u32 v12, v8, 16, 1
	v_pk_mul_f32 v[10:11], v[10:11], v[102:103] op_sel_hi:[1,0]
	v_add3_u32 v8, v8, v12, s1
	v_bfe_u32 v12, v9, 16, 1
	v_pk_fma_f32 v[10:11], v[58:59], v[10:11], v[38:39]
	v_lshrrev_b32_e32 v8, 16, v8
	v_add3_u32 v9, v9, v12, s1
	v_and_or_b32 v8, v9, s2, v8
	v_bfe_u32 v9, v10, 16, 1
	v_add3_u32 v9, v10, v9, s1
	v_bfe_u32 v10, v11, 16, 1
	v_lshrrev_b32_e32 v9, 16, v9
	v_add3_u32 v10, v11, v10, s1
	v_pk_mul_f32 v[4:5], v[4:5], v[102:103] op_sel_hi:[1,0]
	v_and_or_b32 v9, v10, s2, v9
	v_pk_fma_f32 v[4:5], v[60:61], v[4:5], v[44:45]
	global_store_dwordx2 v[94:95], v[8:9], off offset:1024
	v_bfe_u32 v8, v4, 16, 1
	v_pk_mul_f32 v[6:7], v[6:7], v[102:103] op_sel_hi:[1,0]
	v_add3_u32 v4, v4, v8, s1
	v_bfe_u32 v8, v5, 16, 1
	v_pk_fma_f32 v[6:7], v[62:63], v[6:7], v[46:47]
	v_lshrrev_b32_e32 v4, 16, v4
	v_add3_u32 v5, v5, v8, s1
	v_and_or_b32 v4, v5, s2, v4
	v_bfe_u32 v5, v6, 16, 1
	v_add3_u32 v5, v6, v5, s1
	v_bfe_u32 v6, v7, 16, 1
	v_lshrrev_b32_e32 v5, 16, v5
	v_add3_u32 v6, v7, v6, s1
	v_and_or_b32 v5, v6, s2, v5
	global_store_dwordx2 v[94:95], v[4:5], off offset:1536
	v_mov_b32_e32 v16, v28
	v_mov_b32_e32 v17, v29
	v_mov_b32_e32 v18, v30
	v_mov_b32_e32 v19, v31
	v_mov_b32_e32 v12, v24
	v_mov_b32_e32 v13, v25
	v_mov_b32_e32 v14, v26
	v_mov_b32_e32 v15, v27
	v_mov_b32_e32 v8, v20
	v_mov_b32_e32 v9, v21
	v_mov_b32_e32 v10, v22
	v_mov_b32_e32 v11, v23
	v_mov_b32_e32 v4, v0
	v_mov_b32_e32 v5, v1
	v_mov_b32_e32 v6, v2
	v_mov_b32_e32 v7, v3
	v_cmp_ge_i32_e32 vcc, v80, v104
	s_waitcnt vmcnt(4)
	v_mov_b64_e32 v[0:1], v[76:77]
	v_mov_b64_e32 v[20:21], v[72:73]
	v_mov_b64_e32 v[24:25], v[68:69]
	v_mov_b64_e32 v[28:29], v[64:65]
	v_lshl_add_u64 v[94:95], v[94:95], 0, s[14:15]
	s_or_b64 s[12:13], vcc, s[12:13]
	v_mov_b64_e32 v[2:3], v[78:79]
	v_mov_b64_e32 v[22:23], v[74:75]
	v_mov_b64_e32 v[26:27], v[70:71]
	v_mov_b64_e32 v[30:31], v[66:67]
	s_andn2_b64 exec, exec, s[12:13]
	s_cbranch_execz .LBB0_736

; __device__ __forceinline__ unsigned pk2(float lo, float hi) { return f2bf(lo) | (f2bf(hi) << 16); }
; __device__ __forceinline__ float wave_sum(float v) {
; #pragma unroll
;     for (int o = 1; o < 64; o <<= 1) v += __shfl_xor(v, o);
;     return v;
; __device__ __forceinline__ void norm_phase(const float* src, const float* gain, const float* mod_l, int sh_off, int sc_off, bf16_t* dst) {
;     ...
;     for (int row = r0; row < r1; ++row) {
;         const int b = row >> 12;
;         if (b != cur_b) { const float* mb = mod_l + (size_t)b * 6144;
; #pragma unroll
;             for (int j = 0; j < 4; ++j) { const int col = 4 * lane + 256 * j;
;                 cs[j] = *(const f32x4*)(gain + col) * (*(const f32x4*)(mb + sc_off + col) + 1.f); sh[j] = *(const f32x4*)(mb + sh_off + col); }
;             cur_b = b; }
;         f32x4 v[4]; float ss = 0.f;
; #pragma unroll
;         for (int j = 0; j < 4; ++j) { v[j] = vn[j]; vn[j] = vm[j]; }
;         if (row + 2 < r1) { const f32x4* xn = (const f32x4*)(src + (size_t)(row + 2) * DM) + lane;
; #pragma unroll
;             for (int j = 0; j < 4; ++j) vm[j] = xn[64 * j]; }
; #pragma unroll
;         for (int j = 0; j < 4; ++j) ss += (v[j].x * v[j].x + v[j].y * v[j].y) + (v[j].z * v[j].z + v[j].w * v[j].w);
;         const float r = rsqrtf(wave_sum(ss) * (1.f / DM) + RMS_EPS);
;         u32x2* o8 = (u32x2*)(dst + (size_t)row * DM) + lane;
; #pragma unroll
;         for (int j = 0; j < 4; ++j) { const f32x4 y = v[j] * r * cs[j] + sh[j];
;             u32x2 o; o.x = pk2(y[0], y[1]); o.y = pk2(y[2], y[3]); o8[64 * j] = o; }
;     }
.LBB0_1271:
	s_or_b64 exec, exec, s[20:21]
	v_pk_mul_f32 v[102:103], v[12:13], v[12:13]
	v_pk_mul_f32 v[110:111], v[14:15], v[14:15]
	v_pk_mul_f32 v[112:113], v[16:17], v[16:17]
	v_pk_mul_f32 v[114:115], v[18:19], v[18:19]
	v_mov_b32_e32 v116, v112
	v_mov_b32_e32 v117, v115
	v_pk_mov_b32 v[112:113], v[112:113], v[114:115] op_sel:[1,0]
	v_mov_b32_e32 v114, v102
	v_mov_b32_e32 v115, v111
	v_pk_mov_b32 v[102:103], v[102:103], v[110:111] op_sel:[1,0]
	v_pk_add_f32 v[112:113], v[112:113], v[116:117]
	v_pk_add_f32 v[102:103], v[102:103], v[114:115]
	v_pk_add_f32 v[112:113], v[112:113], v[112:113] op_sel_hi:[0,1]
	v_pk_add_f32 v[102:103], v[102:103], v[102:103] op_sel_hi:[0,1]
	v_mul_f32_e32 v102, v8, v8
	v_pk_fma_f32 v[110:111], v[8:9], v[8:9], v[102:103] op_sel_hi:[1,1,0]
	v_mul_f32_e32 v102, v10, v10
	v_pk_fma_f32 v[114:115], v[10:11], v[10:11], v[102:103] op_sel_hi:[1,1,0]
	v_mul_f32_e32 v110, v4, v4
	v_mul_f32_e32 v114, v5, v5
	v_mul_f32_e32 v112, v6, v6
	v_mul_f32_e32 v102, v7, v7
	v_pk_add_f32 v[110:111], v[110:111], v[114:115]
	v_pk_add_f32 v[102:103], v[112:113], v[102:103]
	v_add_u32_e32 v80, 1, v80
	v_pk_add_f32 v[102:103], v[110:111], v[102:103]
	s_nop 0
	v_add_f32_e32 v99, v102, v103
	s_nop 1
	v_add_f32_dpp v99, v99, v99 row_ror:8 row_mask:0xf bank_mask:0xf
	s_nop 1
	v_add_f32_dpp v99, v99, v99 row_ror:4 row_mask:0xf bank_mask:0xf
	s_nop 1
	v_add_f32_dpp v99, v99, v99 row_ror:2 row_mask:0xf bank_mask:0xf
	s_nop 1
	v_add_f32_dpp v99, v99, v99 row_ror:1 row_mask:0xf bank_mask:0xf
	s_nop 1
	v_readlane_b32 s32, v99, 0
	v_readlane_b32 s98, v99, 16
	v_readlane_b32 s99, v99, 32
	v_readlane_b32 s100, v99, 48
	s_nop 0
	v_mov_b32_e32 v99, s32
	v_add_f32_e32 v99, s98, v99
	v_add_f32_e32 v99, s99, v99
	v_add_f32_e32 v99, s100, v99
	v_fmamk_f32 v99, v99, 0x3a800000, v81
	v_mul_f32_e32 v101, 0x4b800000, v99
	v_cmp_gt_f32_e32 vcc, s0, v99
	s_nop 1
	v_cndmask_b32_e32 v99, v99, v101, vcc
	v_rsq_f32_e32 v99, v99
	s_nop 0
	v_mul_f32_e32 v101, 0x45800000, v99
	v_cndmask_b32_e32 v102, v99, v101, vcc
	v_pk_mul_f32 v[16:17], v[16:17], v[102:103] op_sel_hi:[1,0]
	v_pk_mul_f32 v[18:19], v[18:19], v[102:103] op_sel_hi:[1,0]
	v_pk_fma_f32 v[16:17], v[48:49], v[16:17], v[32:33]
	v_pk_fma_f32 v[18:19], v[50:51], v[18:19], v[34:35]
	v_bfe_u32 v99, v16, 16, 1
	v_bfe_u32 v101, v17, 16, 1
	v_bfe_u32 v103, v18, 16, 1
	v_add3_u32 v16, v16, v99, s1
	v_bfe_u32 v109, v19, 16, 1
	v_add3_u32 v17, v17, v101, s1
	v_add3_u32 v18, v18, v103, s1
	v_lshrrev_b32_e32 v16, 16, v16
	v_lshrrev_b32_e32 v18, 16, v18
	v_and_or_b32 v16, v17, s2, v16
	v_add3_u32 v17, v19, v109, s1
	v_pk_mul_f32 v[12:13], v[12:13], v[102:103] op_sel_hi:[1,0]
	v_and_or_b32 v17, v17, s2, v18
	v_pk_fma_f32 v[12:13], v[52:53], v[12:13], v[36:37]
	global_store_dwordx2 v[94:95], v[16:17], off
	v_bfe_u32 v16, v12, 16, 1
	v_pk_mul_f32 v[14:15], v[14:15], v[102:103] op_sel_hi:[1,0]
	v_add3_u32 v12, v12, v16, s1
	v_bfe_u32 v16, v13, 16, 1
	v_pk_fma_f32 v[14:15], v[54:55], v[14:15], v[38:39]
	v_lshrrev_b32_e32 v12, 16, v12
	v_add3_u32 v13, v13, v16, s1
	v_and_or_b32 v12, v13, s2, v12
	v_bfe_u32 v13, v14, 16, 1
	v_add3_u32 v13, v14, v13, s1
	v_bfe_u32 v14, v15, 16, 1
	v_lshrrev_b32_e32 v13, 16, v13
	v_add3_u32 v14, v15, v14, s1
	v_pk_mul_f32 v[8:9], v[8:9], v[102:103] op_sel_hi:[1,0]
	v_and_or_b32 v13, v14, s2, v13
	v_pk_fma_f32 v[8:9], v[56:57], v[8:9], v[40:41]
	global_store_dwordx2 v[94:95], v[12:13], off offset:512
	v_bfe_u32 v12, v8, 16, 1
	v_pk_mul_f32 v[10:11], v[10:11], v[102:103] op_sel_hi:[1,0]
	v_add3_u32 v8, v8, v12, s1
	v_bfe_u32 v12, v9, 16, 1
	v_pk_fma_f32 v[10:11], v[58:59], v[10:11], v[42:43]
	v_lshrrev_b32_e32 v8, 16, v8
	v_add3_u32 v9, v9, v12, s1
	v_and_or_b32 v8, v9, s2, v8
	v_bfe_u32 v9, v10, 16, 1
	v_add3_u32 v9, v10, v9, s1
	v_bfe_u32 v10, v11, 16, 1
	v_lshrrev_b32_e32 v9, 16, v9
	v_add3_u32 v10, v11, v10, s1
	v_pk_mul_f32 v[4:5], v[4:5], v[102:103] op_sel_hi:[1,0]
	v_and_or_b32 v9, v10, s2, v9
	v_pk_fma_f32 v[4:5], v[60:61], v[4:5], v[44:45]
	global_store_dwordx2 v[94:95], v[8:9], off offset:1024
	v_bfe_u32 v8, v4, 16, 1
	v_pk_mul_f32 v[6:7], v[6:7], v[102:103] op_sel_hi:[1,0]
	v_add3_u32 v4, v4, v8, s1
	v_bfe_u32 v8, v5, 16, 1
	v_pk_fma_f32 v[6:7], v[62:63], v[6:7], v[46:47]
	v_lshrrev_b32_e32 v4, 16, v4
	v_add3_u32 v5, v5, v8, s1
	v_and_or_b32 v4, v5, s2, v4
	v_bfe_u32 v5, v6, 16, 1
	v_add3_u32 v5, v6, v5, s1
	v_bfe_u32 v6, v7, 16, 1
	v_lshrrev_b32_e32 v5, 16, v5
	v_add3_u32 v6, v7, v6, s1
	v_and_or_b32 v5, v6, s2, v5
	global_store_dwordx2 v[94:95], v[4:5], off offset:1536
	v_mov_b32_e32 v16, v28
	v_mov_b32_e32 v17, v29
	v_mov_b32_e32 v18, v30
	v_mov_b32_e32 v19, v31
	v_mov_b32_e32 v12, v24
	v_mov_b32_e32 v13, v25
	v_mov_b32_e32 v14, v26
	v_mov_b32_e32 v15, v27
	v_mov_b32_e32 v8, v20
	v_mov_b32_e32 v9, v21
	v_mov_b32_e32 v10, v22
	v_mov_b32_e32 v11, v23
	v_mov_b32_e32 v4, v0
	v_mov_b32_e32 v5, v1
	v_mov_b32_e32 v6, v2
	v_mov_b32_e32 v7, v3
	v_cmp_ge_i32_e32 vcc, v80, v104
	s_waitcnt vmcnt(4)
	v_mov_b64_e32 v[0:1], v[76:77]
	v_mov_b64_e32 v[20:21], v[72:73]
	v_mov_b64_e32 v[24:25], v[68:69]
	v_mov_b64_e32 v[28:29], v[64:65]
	v_lshl_add_u64 v[94:95], v[94:95], 0, s[18:19]
	s_or_b64 s[12:13], vcc, s[12:13]
	v_mov_b64_e32 v[2:3], v[78:79]
	v_mov_b64_e32 v[22:23], v[74:75]
	v_mov_b64_e32 v[26:27], v[70:71]
	v_mov_b64_e32 v[30:31], v[66:67]
	s_andn2_b64 exec, exec, s[12:13]
	s_cbranch_execz .LBB0_1276

; #define LAS __attribute__((address_space(3)))
; __global__ void __launch_bounds__(NTHR, 2) mega_fwd(Params p_unused) {
;     extern __shared__ __attribute__((aligned(16))) unsigned char lds_raw[];
;     LAS unsigned char* lds = (LAS unsigned char*)lds_raw;
	.amdhsa_kernel _Z8mega_fwd6Params
		.amdhsa_group_segment_fixed_size 0
		.amdhsa_private_segment_fixed_size 0
		.amdhsa_kernarg_size 416
		.amdhsa_user_sgpr_count 2
		.amdhsa_user_sgpr_dispatch_ptr 0
		.amdhsa_user_sgpr_queue_ptr 0
		.amdhsa_user_sgpr_kernarg_segment_ptr 1
		.amdhsa_user_sgpr_dispatch_id 0
		.amdhsa_user_sgpr_kernarg_preload_length 0
		.amdhsa_user_sgpr_kernarg_preload_offset 0
		.amdhsa_user_sgpr_private_segment_size 0
		.amdhsa_uses_dynamic_stack 0
		.amdhsa_enable_private_segment 0
		.amdhsa_system_sgpr_workgroup_id_x 1
		.amdhsa_system_sgpr_workgroup_id_y 0
		.amdhsa_system_sgpr_workgroup_id_z 0
		.amdhsa_system_sgpr_workgroup_info 0
		.amdhsa_system_vgpr_workitem_id 2
		.amdhsa_next_free_vgpr 256
		.amdhsa_next_free_sgpr 102
		.amdhsa_accum_offset 256
		.amdhsa_reserve_vcc 1
		.amdhsa_float_round_mode_32 0
		.amdhsa_float_round_mode_16_64 0
		.amdhsa_float_denorm_mode_32 3
		.amdhsa_float_denorm_mode_16_64 3
		.amdhsa_dx10_clamp 1
		.amdhsa_ieee_mode 1
		.amdhsa_fp16_overflow 0
		.amdhsa_tg_split 0
		.amdhsa_exception_fp_ieee_invalid_op 0
		.amdhsa_exception_fp_denorm_src 0
		.amdhsa_exception_fp_ieee_div_zero 0
		.amdhsa_exception_fp_ieee_overflow 0
		.amdhsa_exception_fp_ieee_underflow 0
		.amdhsa_exception_fp_ieee_inexact 0
		.amdhsa_exception_int_div_zero 0
	.end_amdhsa_kernel

; __global__ void __launch_bounds__(NTHR, 2) mega_fwd(Params p_unused) {
amdhsa.kernels:
  - .agpr_count:     0
    .args:
      - .offset:         0
        .size:           160
        .value_kind:     by_value
      - .offset:         160
        .size:           4
        .value_kind:     hidden_block_count_x
      - .offset:         164
        .size:           4
        .value_kind:     hidden_block_count_y
      - .offset:         168
        .size:           4
        .value_kind:     hidden_block_count_z
      - .offset:         172
        .size:           2
        .value_kind:     hidden_group_size_x
      - .offset:         174
        .size:           2
        .value_kind:     hidden_group_size_y
      - .offset:         176
        .size:           2
        .value_kind:     hidden_group_size_z
      - .offset:         178
        .size:           2
        .value_kind:     hidden_remainder_x
      - .offset:         180
        .size:           2
        .value_kind:     hidden_remainder_y
      - .offset:         182
        .size:           2
        .value_kind:     hidden_remainder_z
      - .offset:         200
        .size:           8
        .value_kind:     hidden_global_offset_x
      - .offset:         208
        .size:           8
        .value_kind:     hidden_global_offset_y
      - .offset:         216
        .size:           8
        .value_kind:     hidden_global_offset_z
      - .offset:         224
        .size:           2
        .value_kind:     hidden_grid_dims
      - .offset:         248
        .size:           8
        .value_kind:     hidden_multigrid_sync_arg
      - .offset:         280
        .size:           4
        .value_kind:     hidden_dynamic_lds_size
    .group_segment_fixed_size: 0
    .kernarg_segment_align: 8
    .kernarg_segment_size: 416
    .language:       OpenCL C
    .language_version:
      - 2
      - 0
    .max_flat_workgroup_size: 512
    .name:           _Z8mega_fwd6Params
    .private_segment_fixed_size: 0
    .sgpr_count:     108
    .sgpr_spill_count: 24
    .symbol:         _Z8mega_fwd6Params.kd
    .uniform_work_group_size: 1
    .uses_dynamic_stack: false
    .vgpr_count:     256
    .vgpr_spill_count: 0
    .wavefront_size: 64
